# P3 queue order: memory-attention items first, smallest causal items last
# baseline (speedup 1.0000x reference)
;     constexpr int KS = DQK + 8, NKS = DQK / 16, KCH = DQK / 8, NKL = 64 * KCH / 256;
; DI void phase3(const Params& p, int l, unsigned char* smem, unsigned char* smem0) {
;     ...
;         __syncthreads();
;         const int code = *s_item;
;         if (code < 0) break;
;         const int x = code >> 8, idx = code & 255, bh = x + 8 * hf, b = bh >> 2, head = bh & 3;
;         if (idx < 192) {
;             const int qb = 63 - idx / 3, r3 = idx % 3, br = (r3 == 0) ? 1 : (r3 == 1 ? 2 : 0), q0 = qb * 128, nt = 2 * qb + 2;
;             if (br == 0) {
;                 attn_item<64, 1, true>((const bf16_t*)(ws + O_SBQ) + ((size_t)bh * S_ + q0) * 64, (const bf16_t*)(ws + O_SBK) + (size_t)bh * S_ * 64,
;                                  (const bf16_t*)(ws + O_SBVT) + (size_t)bh * 64 * S_, S_, nullptr, q0, nt, GATE + ((size_t)b * S_ + q0) * 1024 + 256 + head * 64, YBo + ((size_t)b * S_ + q0) * 1024 + 256 + head * 64, smem, smem0, hf);
;             } else if (br == 1) {
;                 attn_item<96, 0, false>((const bf16_t*)(ws + O_MQ) + ((size_t)bh * S_ + q0) * 96, (const bf16_t*)(ws + O_MK) + (size_t)bh * S_ * 96,
;                                  (const bf16_t*)(ws + O_MVT) + (size_t)bh * 64 * S_, S_, nullptr, q0, nt, GATE + ((size_t)b * S_ + q0) * 1024 + head * 64, YBo + ((size_t)b * S_ + q0) * 1024 + head * 64, smem, smem0, hf);
;             } else {
;                 attn_item<64, 0, true>((const bf16_t*)(ws + O_FQ) + ((size_t)bh * S_ + q0) * 64, (const bf16_t*)(ws + O_FK) + (size_t)bh * S_ * 64,
;                                  (const bf16_t*)(ws + O_FVT) + (size_t)bh * 64 * S_, S_, (const float*)(ws + O_FC) + (size_t)bh * S_, q0, nt,
;                                  GATE + ((size_t)b * S_ + q0) * 1024 + 512 + head * 64, YBo + ((size_t)b * S_ + q0) * 1024 + 512 + head * 64, smem, smem0, hf,
;                                  sqrtf(((const float*)(ws + O_KMAX))[bh]) * 1.0002f);
;             }
;         } else {
;             const int qb = idx - 192, q0 = qb * 128;
;             attn_item<64, 2, false>((const bf16_t*)(ws + O_MEMQ) + ((size_t)bh * S_ + q0) * 64, (const bf16_t*)(ws + O_MEMK) + (size_t)bh * 256 * 64,
;                              (const bf16_t*)(ws + O_MEMVT) + (size_t)bh * 64 * 256, 256, nullptr, q0, 4, GATE + ((size_t)b * S_ + q0) * 1024 + 768 + head * 64, YBo + ((size_t)b * S_ + q0) * 1024 + 768 + head * 64, smem, smem0, hf);
.LBB0_720:
	s_or_b64 exec, exec, s[4:5]
	s_waitcnt lgkmcnt(0)
	s_barrier
	ds_read_b32 v0, v219
	s_waitcnt lgkmcnt(0)
	v_cmp_gt_i32_e32 vcc, 0, v0
	v_readfirstlane_b32 s8, v0
	s_cbranch_vccnz .LBB0_730
	s_add_i32 s4, s8, 0xc0
	s_and_b32 s4, s4, 0xff
	s_andn2_b32 s8, s8, 0xff
	s_or_b32 s8, s8, s4
	s_lshr_b32 s4, s8, 8
	s_add_i32 s10, s4, s72
	s_and_b32 s9, s8, 0xff
	s_lshr_b32 s56, s10, 2
	s_bfe_u32 s79, s8, 0x20008
	s_cmpk_gt_u32 s9, 0xbf
	s_mov_b64 s[4:5], -1
	s_cbranch_scc0 .LBB0_732
	s_lshl_b32 s4, s9, 7
	s_mov_b32 s11, s49
	s_add_i32 s48, s4, 0xffffa000
	s_lshl_b64 s[4:5], s[10:11], 20
	s_add_u32 s6, s73, s4
	s_addc_u32 s7, s74, s5
	s_lshl_b64 s[4:5], s[48:49], 7
	s_add_u32 s6, s6, s4
	s_addc_u32 s7, s7, s5
	s_lshl_b64 s[4:5], s[10:11], 15
	v_mov_b32_e32 v14, v215
	s_add_u32 s12, s75, s4
	s_addc_u32 s13, s87, s5
	v_lshlrev_b32_e32 v2, 4, v14
	v_lshlrev_b32_e32 v0, 6, v14
	v_and_b32_e32 v3, 0x70, v2
	s_movk_i32 s11, 0xfe00
	s_add_u32 s14, s62, s4
	v_and_or_b32 v4, v0, s11, v3
	v_mov_b32_e32 v3, v1
	v_add_u32_e32 v8, 0x1000, v2
	v_mov_b32_e32 v9, v1
	v_ashrrev_i32_e32 v0, 1, v14
	s_addc_u32 s15, s3, s5
	v_lshl_add_u64 v[6:7], s[12:13], 0, v[2:3]
	v_lshl_add_u64 v[10:11], s[12:13], 0, v[8:9]
	v_mov_b32_e32 v5, v1
	v_bfi_b32 v98, s41, v0, v14
	global_load_dwordx4 v[66:69], v[6:7], off
	global_load_dwordx4 v[70:73], v[10:11], off
	v_lshl_add_u64 v[6:7], s[14:15], 0, v[4:5]
	v_add_u32_e32 v10, 0x4000, v4
	v_mov_b32_e32 v11, v1
	v_ashrrev_i32_e32 v99, 31, v98
	v_lshl_add_u64 v[12:13], s[14:15], 0, v[10:11]
	global_load_dwordx4 v[74:77], v[6:7], off
	global_load_dwordx4 v[78:81], v[12:13], off
	v_bfe_u32 v101, v14, 5, 1
	v_lshlrev_b64 v[6:7], 7, v[98:99]
	v_lshl_add_u64 v[6:7], s[6:7], 0, v[6:7]
	v_lshlrev_b32_e32 v0, 4, v101
	v_lshl_add_u64 v[6:7], v[6:7], 0, v[0:1]
	global_load_dwordx4 v[82:85], v[6:7], off
	global_load_dwordx4 v[86:89], v[6:7], off offset:32
	global_load_dwordx4 v[90:93], v[6:7], off offset:64
	global_load_dwordx4 v[94:97], v[6:7], off offset:96
	v_ashrrev_i32_e32 v7, 31, v14
	v_add_u32_e32 v12, 0x100, v14
	v_and_b32_e32 v6, 31, v14
	v_lshrrev_b32_e32 v13, 3, v14
	v_lshlrev_b32_e32 v15, 3, v14
	v_lshrrev_b32_e32 v7, 29, v7
	v_ashrrev_i32_e32 v16, 31, v12
	s_movk_i32 s0, 0x48
	v_and_b32_e32 v15, 56, v15
	v_mul_lo_u32 v13, v13, s0
	v_lshrrev_b32_e32 v17, 3, v12
	v_mul_u32_u24_e32 v6, 0x48, v6
	v_add_u32_e32 v7, v14, v7
	v_lshrrev_b32_e32 v16, 29, v16
	v_lshlrev_b32_e32 v111, 1, v13
	v_lshlrev_b32_e32 v112, 1, v15
	v_mul_lo_u32 v13, v17, s0
	v_lshlrev_b32_e32 v6, 1, v6
	v_lshrrev_b32_e32 v15, 3, v7
	v_and_b32_e32 v7, -8, v7
	v_add_u32_e32 v16, v12, v16
	v_lshlrev_b32_e32 v113, 1, v13
	v_add3_u32 v114, s33, v6, v0
	v_sub_u32_e32 v0, v14, v7
	v_mul_lo_u32 v6, v15, s0
	v_lshrrev_b32_e32 v7, 3, v16
	v_and_b32_e32 v13, -8, v16
	v_lshlrev_b32_e32 v16, 3, v0
	v_lshlrev_b32_e32 v115, 1, v6
	v_lshlrev_b32_e32 v0, 4, v0
	v_sub_u32_e32 v6, v12, v13
	v_mul_lo_u32 v7, v7, s0
	v_add3_u32 v14, s33, v113, v112
	v_add3_u32 v0, s33, v115, v0
	v_lshlrev_b32_e32 v18, 3, v6
	v_lshlrev_b32_e32 v116, 1, v7
	v_lshlrev_b32_e32 v6, 4, v6
	v_add3_u32 v17, s33, v111, v112
	v_add3_u32 v6, s33, v116, v6
	s_waitcnt lgkmcnt(0)
	s_barrier
	v_mov_b32_e32 v15, v1
	v_lshl_add_u64 v[102:103], s[52:53], 0, v[10:11]
	v_lshl_add_u64 v[104:105], s[52:53], 0, v[4:5]
	v_lshl_add_u64 v[106:107], s[54:55], 0, v[8:9]
	v_lshl_add_u64 v[108:109], s[54:55], 0, v[2:3]
	v_mov_b32_e32 v2, v1
	v_mov_b32_e32 v4, v1
	s_waitcnt vmcnt(0)
	ds_write_b128 v0, v[66:69]
	ds_write_b128 v6, v[70:73]
	ds_write_b128 v17, v[74:77] offset:13312
	ds_write_b128 v14, v[78:81] offset:13312
	v_mov_b32_e32 v14, v1
	v_mov_b32_e32 v0, v1
	v_mov_b32_e32 v6, v1
	v_mov_b32_e32 v7, v1
	v_mov_b32_e32 v8, v1
	v_mov_b32_e32 v10, v1
	v_mov_b32_e32 v12, v1
	v_mov_b32_e32 v13, v1
	v_lshlrev_b32_e32 v119, 1, v18
	v_mov_b64_e32 v[32:33], v[14:15]
	v_lshlrev_b32_e32 v100, 3, v101
	v_lshlrev_b32_e32 v118, 1, v16
	v_mov_b64_e32 v[30:31], v[12:13]
	v_mov_b64_e32 v[28:29], v[10:11]
	v_mov_b64_e32 v[26:27], v[8:9]
	v_mov_b64_e32 v[24:25], v[6:7]
	v_mov_b64_e32 v[22:23], v[4:5]
	v_mov_b64_e32 v[20:21], v[2:3]
	v_mov_b64_e32 v[18:19], v[0:1]
	v_mov_b64_e32 v[16:17], v[14:15]
	s_mov_b32 s11, 0
	v_sub_u32_e32 v117, 0, v100
	v_mov_b32_e32 v120, 0
	v_mov_b32_e32 v110, 0xff800000
	v_mov_b64_e32 v[14:15], v[12:13]
	v_mov_b64_e32 v[12:13], v[10:11]
	v_mov_b64_e32 v[10:11], v[8:9]
	v_mov_b64_e32 v[8:9], v[6:7]
	v_mov_b64_e32 v[6:7], v[4:5]
	v_mov_b64_e32 v[4:5], v[2:3]
	v_mov_b64_e32 v[2:3], v[0:1]
	s_cmp_lg_u32 s11, 3
	s_cselect_b64 s[6:7], -1, 0
	s_cmp_eq_u32 s11, 3
	s_cbranch_scc1 .LBB0_724
